# v18 + MLA loop: accumulator -max broadcast init via v_pk_mov_b32 (16 VALU ops instead of 32 per kv step)
# speedup vs baseline: 1.0026x; 1.0026x over previous
; #define MFMA32(a, b, c) __builtin_amdgcn_mfma_f32_32x32x16_bf16((a), (b), (c), 0, 0, 0)
; #define ALOAD(i) { const int kk0 = TILE_K0(i); \
;     kr0 = *(const uint4*)(Kb + (size_t)(kk0 + krow0) * DQK + kcc0 * 8); \
;     if (K2) kr1 = *(const uint4*)(Kb + (size_t)(kk0 + krow1) * DQK + kcc1 * 8); \
;     vr0 = *(const uint4*)(Vb + (size_t)vrow0 * TT + kk0 + vcc0 * 8); }
; #define ASTORE(bb) { bf16_t* dK = (bf16_t*)smem + (bb) * BUFE; bf16_t* dV = dK + 64 * KSTR; \
;     *(uint4*)(dK + krow0 * KSTR + kcc0 * 8) = kr0; \
;     if (K2) *(uint4*)(dK + krow1 * KSTR + kcc1 * 8) = kr1; \
;     *(uint4*)(dV + vrow0 * VSTR + vcc0 * 8) = vr0; }
; #define ASTORE(bb) { bf16_t* dK = (bf16_t*)smem + (bb) * BUFE; bf16_t* dV = dK + 64 * KSTR; \
;     *(uint4*)(dK + krow0 * KSTR + kcc0 * 8) = kr0; \
;     if (K2) *(uint4*)(dK + krow1 * KSTR + kcc1 * 8) = kr1; \
;     *(uint4*)(dV + vrow0 * VSTR + vcc0 * 8) = vr0; }
; template <int DQK>
; DI void attn_item2(char* smem, const bf16_t* __restrict__ Q, const bf16_t* __restrict__ K, const bf16_t* __restrict__ VT,
;                    int qh, int kvh, int b, int q0, bf16_t* __restrict__ Y, int ycol) {
;     ...
;   for (int it = 0; it < ntiles; ++it) {
;     __syncthreads();
;     const bf16_t* sK = (const bf16_t*)smem + (it & 1) * BUFE;
;     const bf16_t* sV = sK + 64 * KSTR;
;     f32x16 s[2][2];
; #pragma unroll
;     for (int qn = 0; qn < 2; ++qn) {
;       const float ninit = -m[qn];
; #pragma unroll
;       for (int i = 0; i < 16; ++i) { s[qn][0][i] = ninit; s[qn][1][i] = ninit; }
;     }
; #pragma unroll
;     for (int ks = 0; ks < KS; ++ks) {
;       bf16x8 a0 = *(const bf16x8*)(sK + r * KSTR + ks * 16 + 8 * h);
;       bf16x8 a1 = *(const bf16x8*)(sK + (32 + r) * KSTR + ks * 16 + 8 * h);
; #pragma unroll
;       for (int qn = 0; qn < 2; ++qn) {
;         s[qn][0] = MFMA32(a0, qf[qn][ks], s[qn][0]);
;         s[qn][1] = MFMA32(a1, qf[qn][ks], s[qn][1]);
;       }
;     }
;     __builtin_amdgcn_sched_barrier(0);
;     ASTORE((it + 1) & 1)
;     __builtin_amdgcn_sched_barrier(0);
;     ALOAD(min(it + 2, ntiles - 1))
;     __builtin_amdgcn_sched_barrier(0);
;     int mxb = __float_as_int(s[0][0][0]);
; #pragma unroll
;     for (int qn = 0; qn < 2; ++qn)
; #pragma unroll
;       for (int i = 0; i < 16; ++i) mxb = max(mxb, max(__float_as_int(s[qn][0][i]), __float_as_int(s[qn][1][i])));
;     if (__any((it == 0) || (mxb > 0x41000000))) {
.LBB0_160:
	s_add_i32 s7, s2, -1
	s_bitcmp1_b32 s7, 0
	s_cselect_b32 s3, 0x5800, 0
	s_add_i32 s3, s3, 0
	v_add3_u32 v192, s3, v236, v220
	s_barrier
	ds_read_b128 v[216:219], v192
	ds_read_b128 v[222:225], v192 offset:6656
	v_xor_b32_e32 v82, 0x80000000, v213
	v_xor_b32_e32 v66, 0x80000000, v212
	v_mov_b32_e32 v83, v82
	v_pk_mov_b32 v[84:85], v[82:83], v[82:83] op_sel:[0,0] op_sel_hi:[0,0]
	v_pk_mov_b32 v[86:87], v[82:83], v[82:83] op_sel:[0,0] op_sel_hi:[0,0]
	v_pk_mov_b32 v[88:89], v[82:83], v[82:83] op_sel:[0,0] op_sel_hi:[0,0]
	v_pk_mov_b32 v[90:91], v[82:83], v[82:83] op_sel:[0,0] op_sel_hi:[0,0]
	v_pk_mov_b32 v[92:93], v[82:83], v[82:83] op_sel:[0,0] op_sel_hi:[0,0]
	v_pk_mov_b32 v[94:95], v[82:83], v[82:83] op_sel:[0,0] op_sel_hi:[0,0]
	v_pk_mov_b32 v[96:97], v[82:83], v[82:83] op_sel:[0,0] op_sel_hi:[0,0]
	v_mov_b32_e32 v67, v66
	v_pk_mov_b32 v[68:69], v[66:67], v[66:67] op_sel:[0,0] op_sel_hi:[0,0]
	v_pk_mov_b32 v[70:71], v[66:67], v[66:67] op_sel:[0,0] op_sel_hi:[0,0]
	v_pk_mov_b32 v[72:73], v[66:67], v[66:67] op_sel:[0,0] op_sel_hi:[0,0]
	v_pk_mov_b32 v[74:75], v[66:67], v[66:67] op_sel:[0,0] op_sel_hi:[0,0]
	v_pk_mov_b32 v[76:77], v[66:67], v[66:67] op_sel:[0,0] op_sel_hi:[0,0]
	v_pk_mov_b32 v[78:79], v[66:67], v[66:67] op_sel:[0,0] op_sel_hi:[0,0]
	v_pk_mov_b32 v[80:81], v[66:67], v[66:67] op_sel:[0,0] op_sel_hi:[0,0]
	s_waitcnt lgkmcnt(1)
	v_mfma_f32_32x32x16_bf16 v[114:129], v[216:219], v[130:133], v[82:97]
	s_waitcnt lgkmcnt(0)
	v_mfma_f32_32x32x16_bf16 v[82:97], v[222:225], v[130:133], v[82:97]
	v_mfma_f32_32x32x16_bf16 v[98:113], v[216:219], v[154:157], v[66:81]
	ds_read_b128 v[216:219], v192 offset:32
	v_mfma_f32_32x32x16_bf16 v[66:81], v[222:225], v[154:157], v[66:81]
	ds_read_b128 v[222:225], v192 offset:6688
	s_waitcnt lgkmcnt(1)
	v_mfma_f32_32x32x16_bf16 v[114:129], v[216:219], v[134:137], v[114:129]
	s_waitcnt lgkmcnt(0)
	v_mfma_f32_32x32x16_bf16 v[82:97], v[222:225], v[134:137], v[82:97]
	v_mfma_f32_32x32x16_bf16 v[98:113], v[216:219], v[158:161], v[98:113]
	ds_read_b128 v[216:219], v192 offset:64
	v_mfma_f32_32x32x16_bf16 v[66:81], v[222:225], v[158:161], v[66:81]
	ds_read_b128 v[222:225], v192 offset:6720
	s_waitcnt lgkmcnt(1)
	v_mfma_f32_32x32x16_bf16 v[114:129], v[216:219], v[138:141], v[114:129]
	s_waitcnt lgkmcnt(0)
	v_mfma_f32_32x32x16_bf16 v[82:97], v[222:225], v[138:141], v[82:97]
	v_mfma_f32_32x32x16_bf16 v[98:113], v[216:219], v[162:165], v[98:113]
	ds_read_b128 v[216:219], v192 offset:96
	v_mfma_f32_32x32x16_bf16 v[66:81], v[222:225], v[162:165], v[66:81]
	ds_read_b128 v[222:225], v192 offset:6752
	s_waitcnt lgkmcnt(1)
	v_mfma_f32_32x32x16_bf16 v[114:129], v[216:219], v[142:145], v[114:129]
	s_waitcnt lgkmcnt(0)
	v_mfma_f32_32x32x16_bf16 v[82:97], v[222:225], v[142:145], v[82:97]
	v_mfma_f32_32x32x16_bf16 v[98:113], v[216:219], v[166:169], v[98:113]
	ds_read_b128 v[216:219], v192 offset:128
	v_mfma_f32_32x32x16_bf16 v[66:81], v[222:225], v[166:169], v[66:81]
	ds_read_b128 v[222:225], v192 offset:6784
	s_waitcnt lgkmcnt(1)
	v_mfma_f32_32x32x16_bf16 v[114:129], v[216:219], v[146:149], v[114:129]
	s_waitcnt lgkmcnt(0)
	v_mfma_f32_32x32x16_bf16 v[82:97], v[222:225], v[146:149], v[82:97]
	v_mfma_f32_32x32x16_bf16 v[98:113], v[216:219], v[170:173], v[98:113]
	ds_read_b128 v[216:219], v192 offset:160
	v_mfma_f32_32x32x16_bf16 v[66:81], v[222:225], v[170:173], v[66:81]
	ds_read_b128 v[222:225], v192 offset:6816
	s_waitcnt lgkmcnt(1)
	v_mfma_f32_32x32x16_bf16 v[114:129], v[216:219], v[150:153], v[114:129]
	s_waitcnt lgkmcnt(0)
	v_mfma_f32_32x32x16_bf16 v[82:97], v[222:225], v[150:153], v[82:97]
	v_mfma_f32_32x32x16_bf16 v[98:113], v[216:219], v[174:177], v[98:113]
	v_mfma_f32_32x32x16_bf16 v[66:81], v[222:225], v[174:177], v[66:81]
	s_bitcmp1_b32 s2, 0
	s_cselect_b32 s8, 0x5800, 0
	s_add_i32 s8, s8, 0
	v_lshlrev_b32_e32 v192, 1, v200
	v_add3_u32 v192, s8, v201, v192
	s_waitcnt vmcnt(2)
	ds_write_b128 v192, v[186:189]
	v_lshlrev_b32_e32 v186, 1, v202
	s_min_i32 s7, s7, 0x81
	v_add3_u32 v188, s8, v203, v186
	v_add3_u32 v189, s8, v205, v204
	s_lshl_b32 s8, s7, 6
	s_add_i32 s10, s8, 0x80
	v_add_u32_e32 v186, s10, v241
	v_mad_i64_i32 v[186:187], s[8:9], v186, s0, v[208:209]
	v_add_u32_e32 v192, s10, v242
	v_mad_i64_i32 v[216:217], s[8:9], v192, s0, v[210:211]
	s_waitcnt vmcnt(1)
	ds_write_b128 v188, v[178:181]
	s_waitcnt vmcnt(0)
	ds_write_b128 v189, v[182:185] offset:13312
	s_lshl_b32 s88, s7, 7
	v_lshl_add_u64 v[182:183], v[206:207], 0, s[88:89]
	global_load_dwordx4 v[186:189], v[186:187], off
	s_nop 0
	global_load_dwordx4 v[178:181], v[216:217], off
	s_nop 0
	global_load_dwordx4 v[182:185], v[182:183], off offset:256
	v_max_i32_e32 v192, v115, v83
	v_max3_i32 v192, v114, v82, v192
	v_max_i32_e32 v193, v116, v84
	v_max_i32_e32 v216, v117, v85
	v_max3_i32 v192, v192, v193, v216
	v_max_i32_e32 v193, v118, v86
	v_max_i32_e32 v216, v119, v87
	v_max3_i32 v192, v192, v193, v216
	v_max_i32_e32 v193, v120, v88
	v_max_i32_e32 v216, v121, v89
	v_max3_i32 v192, v192, v193, v216
	v_max_i32_e32 v193, v122, v90
	v_max_i32_e32 v216, v123, v91
	v_max3_i32 v192, v192, v193, v216
	v_max_i32_e32 v193, v124, v92
	v_max_i32_e32 v216, v125, v93
	v_max3_i32 v192, v192, v193, v216
	v_max_i32_e32 v193, v126, v94
	v_max_i32_e32 v216, v127, v95
	v_max3_i32 v192, v192, v193, v216
	v_max_i32_e32 v193, v128, v96
	v_max_i32_e32 v216, v129, v97
	v_max3_i32 v192, v192, v193, v216
	v_max_i32_e32 v193, v98, v66
	v_max_i32_e32 v216, v99, v67
	v_max3_i32 v192, v192, v193, v216
	v_max_i32_e32 v193, v100, v68
	v_max_i32_e32 v216, v101, v69
	v_max3_i32 v192, v192, v193, v216
	v_max_i32_e32 v193, v102, v70
	v_max_i32_e32 v216, v103, v71
	v_max3_i32 v192, v192, v193, v216
	v_max_i32_e32 v193, v104, v72
	v_max_i32_e32 v216, v105, v73
	v_max3_i32 v192, v192, v193, v216
	v_max_i32_e32 v193, v106, v74
	v_max_i32_e32 v216, v107, v75
	v_max3_i32 v192, v192, v193, v216
	v_max_i32_e32 v193, v108, v76
	v_max_i32_e32 v216, v109, v77
	v_max3_i32 v192, v192, v193, v216
	v_max_i32_e32 v193, v110, v78
	v_max_i32_e32 v216, v111, v79
	v_max3_i32 v192, v192, v193, v216
	v_max_i32_e32 v193, v112, v80
	v_max_i32_e32 v216, v113, v81
	v_max3_i32 v192, v192, v193, v216
	s_mov_b32 s7, 0x41000000
	v_cmp_lt_i32_e32 vcc, s7, v192
	s_cbranch_vccz .LBB0_159
; template <int DQK>
; DI void attn_item2(char* smem, const bf16_t* __restrict__ Q, const bf16_t* __restrict__ K, const bf16_t* __restrict__ VT,
;                    int qh, int kvh, int b, int q0, bf16_t* __restrict__ Y, int ycol) {
;     ...
;     if (__any((it == 0) || (mxb > 0x41000000))) {
; #pragma unroll
;       for (int qn = 0; qn < 2; ++qn) {
;         float mx = -1e30f;
; #pragma unroll
;         for (int i = 0; i < 16; ++i) mx = fmaxf(mx, fmaxf(s[qn][0][i], s[qn][1][i]));
;         mx = fmaxf(mx, __shfl_xor(mx, 32, 64));
;         const float delta = (it == 0) ? mx : fmaxf(mx, 0.f);
;         const float alpha = (it == 0) ? 1.f : __builtin_amdgcn_exp2f(-delta);
;         m[qn] += delta;
;         lsum[qn] *= alpha;
; #pragma unroll
;         for (int i = 0; i < 16; ++i) { o[qn][0][i] *= alpha; o[qn][1][i] *= alpha; s[qn][0][i] -= delta; s[qn][1][i] -= delta; }
;       }
	v_and_b32_e32 v193, 64, v1
	v_xor_b32_e32 v192, 32, v1
	v_add_u32_e32 v193, 64, v193
	v_cmp_lt_i32_e32 vcc, v192, v193
	v_max_f32_e32 v193, v82, v82
	v_max_f32_e32 v216, v114, v114
	v_max_f32_e32 v193, v216, v193
	v_max_f32_e32 v216, v83, v83
	v_max_f32_e32 v217, v115, v115
	v_max_f32_e32 v216, v217, v216
	s_mov_b32 s7, 0xf149f2ca
	v_max3_f32 v193, v193, s7, v216
	v_max_f32_e32 v216, v84, v84
	v_max_f32_e32 v217, v116, v116
	v_max_f32_e32 v216, v217, v216
	v_max_f32_e32 v217, v85, v85
	v_max_f32_e32 v218, v117, v117
	v_max_f32_e32 v217, v218, v217
	v_max3_f32 v193, v193, v216, v217
	v_max_f32_e32 v216, v86, v86
	v_max_f32_e32 v217, v118, v118
	v_max_f32_e32 v216, v217, v216
	v_max_f32_e32 v217, v87, v87
	v_max_f32_e32 v218, v119, v119
	v_max_f32_e32 v217, v218, v217
	v_max3_f32 v193, v193, v216, v217
	v_max_f32_e32 v216, v88, v88
	v_max_f32_e32 v217, v120, v120
	v_max_f32_e32 v216, v217, v216
	v_max_f32_e32 v217, v89, v89
	v_max_f32_e32 v218, v121, v121
	v_max_f32_e32 v217, v218, v217
	v_max3_f32 v193, v193, v216, v217
	v_max_f32_e32 v216, v90, v90
	v_max_f32_e32 v217, v122, v122
	v_max_f32_e32 v216, v217, v216
	v_max_f32_e32 v217, v91, v91
	v_max_f32_e32 v218, v123, v123
	v_max_f32_e32 v217, v218, v217
	v_max3_f32 v193, v193, v216, v217
	v_max_f32_e32 v216, v92, v92
	v_max_f32_e32 v217, v124, v124
	v_max_f32_e32 v216, v217, v216
	v_max_f32_e32 v217, v93, v93
	v_max_f32_e32 v218, v125, v125
	v_max_f32_e32 v217, v218, v217
	v_max3_f32 v193, v193, v216, v217
	v_max_f32_e32 v216, v94, v94
	v_max_f32_e32 v217, v126, v126
	v_max_f32_e32 v216, v217, v216
	v_max_f32_e32 v217, v95, v95
	v_max_f32_e32 v218, v127, v127
	v_max_f32_e32 v217, v218, v217
	v_max3_f32 v193, v193, v216, v217
	v_max_f32_e32 v216, v96, v96
	v_max_f32_e32 v217, v128, v128
	v_max_f32_e32 v216, v217, v216
	v_max_f32_e32 v217, v97, v97
	v_max_f32_e32 v218, v129, v129
	v_cndmask_b32_e32 v192, v1, v192, vcc
	v_max_f32_e32 v217, v218, v217
	v_lshlrev_b32_e32 v192, 2, v192
	v_max3_f32 v193, v193, v216, v217
	ds_bpermute_b32 v216, v192, v193
	v_max_f32_e32 v221, v101, v101
	s_waitcnt lgkmcnt(0)
	v_max3_f32 v217, v193, v216, 0
	v_exp_f32_e64 v218, -v217
	v_max_f32_e32 v193, v66, v66
	v_max_f32_e32 v216, v98, v98
	v_max_f32_e32 v193, v216, v193
	v_pk_mul_f32 v[48:49], v[48:49], v[218:219] op_sel_hi:[1,0]
	v_pk_mul_f32 v[46:47], v[46:47], v[218:219] op_sel_hi:[1,0]
	v_pk_mul_f32 v[44:45], v[44:45], v[218:219] op_sel_hi:[1,0]
	v_pk_mul_f32 v[42:43], v[42:43], v[218:219] op_sel_hi:[1,0]
	v_pk_mul_f32 v[40:41], v[40:41], v[218:219] op_sel_hi:[1,0]
	v_pk_mul_f32 v[38:39], v[38:39], v[218:219] op_sel_hi:[1,0]
	v_pk_mul_f32 v[36:37], v[36:37], v[218:219] op_sel_hi:[1,0]
	v_pk_mul_f32 v[34:35], v[34:35], v[218:219] op_sel_hi:[1,0]
	v_pk_mul_f32 v[64:65], v[64:65], v[218:219] op_sel_hi:[1,0]
	v_pk_mul_f32 v[62:63], v[62:63], v[218:219] op_sel_hi:[1,0]
	v_pk_mul_f32 v[60:61], v[60:61], v[218:219] op_sel_hi:[1,0]
	v_pk_mul_f32 v[58:59], v[58:59], v[218:219] op_sel_hi:[1,0]
	v_pk_mul_f32 v[56:57], v[56:57], v[218:219] op_sel_hi:[1,0]
	v_pk_mul_f32 v[54:55], v[54:55], v[218:219] op_sel_hi:[1,0]
	v_pk_mul_f32 v[52:53], v[52:53], v[218:219] op_sel_hi:[1,0]
	v_pk_mul_f32 v[50:51], v[50:51], v[218:219] op_sel_hi:[1,0]
	v_max_f32_e32 v216, v67, v67
	v_max_f32_e32 v219, v99, v99
	v_max_f32_e32 v216, v219, v216
	v_max3_f32 v193, v193, s7, v216
	v_max_f32_e32 v216, v68, v68
	v_max_f32_e32 v219, v100, v100
	v_max_f32_e32 v216, v219, v216
	v_max_f32_e32 v219, v69, v69
	v_max_f32_e32 v219, v221, v219
	v_max3_f32 v193, v193, v216, v219
	v_max_f32_e32 v216, v70, v70
	v_max_f32_e32 v219, v102, v102
	v_max_f32_e32 v216, v219, v216
	v_max_f32_e32 v219, v71, v71
	v_max_f32_e32 v221, v103, v103
	v_max_f32_e32 v219, v221, v219
	v_max3_f32 v193, v193, v216, v219
	v_max_f32_e32 v216, v72, v72
	v_max_f32_e32 v219, v104, v104
	v_max_f32_e32 v216, v219, v216
	v_max_f32_e32 v219, v73, v73
	v_max_f32_e32 v221, v105, v105
	v_max_f32_e32 v219, v221, v219
	v_max3_f32 v193, v193, v216, v219
	v_max_f32_e32 v216, v74, v74
	v_max_f32_e32 v219, v106, v106
	v_max_f32_e32 v216, v219, v216
	v_max_f32_e32 v219, v75, v75
	v_max_f32_e32 v221, v107, v107
	v_max_f32_e32 v219, v221, v219
	v_max3_f32 v193, v193, v216, v219
	v_max_f32_e32 v216, v76, v76
	v_max_f32_e32 v219, v108, v108
	v_max_f32_e32 v216, v219, v216
	v_max_f32_e32 v219, v77, v77
	v_max_f32_e32 v221, v109, v109
	v_max_f32_e32 v219, v221, v219
	v_max3_f32 v193, v193, v216, v219
	v_max_f32_e32 v216, v78, v78
	v_max_f32_e32 v219, v110, v110
	v_max_f32_e32 v216, v219, v216
	v_max_f32_e32 v219, v79, v79
	v_max_f32_e32 v221, v111, v111
	v_max_f32_e32 v219, v221, v219
	v_max3_f32 v193, v193, v216, v219
	v_max_f32_e32 v216, v80, v80
	v_max_f32_e32 v219, v112, v112
	v_max_f32_e32 v216, v219, v216
	v_max_f32_e32 v219, v81, v81
	v_max_f32_e32 v221, v113, v113
	v_max_f32_e32 v219, v221, v219
	v_max3_f32 v193, v193, v216, v219
	ds_bpermute_b32 v192, v192, v193
	v_mov_b32_e32 v223, v218
	v_sub_f32_e32 v129, v129, v217
	v_sub_f32_e32 v128, v128, v217
	v_sub_f32_e32 v127, v127, v217
	s_waitcnt lgkmcnt(0)
; template <int DQK>
; DI void attn_item2(char* smem, const bf16_t* __restrict__ Q, const bf16_t* __restrict__ K, const bf16_t* __restrict__ VT,
;                    int qh, int kvh, int b, int q0, bf16_t* __restrict__ Y, int ycol) {
;     ...
;       for (int qn = 0; qn < 2; ++qn) {
;         float mx = -1e30f;
; #pragma unroll
;         for (int i = 0; i < 16; ++i) mx = fmaxf(mx, fmaxf(s[qn][0][i], s[qn][1][i]));
;         mx = fmaxf(mx, __shfl_xor(mx, 32, 64));
;         const float delta = (it == 0) ? mx : fmaxf(mx, 0.f);
;         const float alpha = (it == 0) ? 1.f : __builtin_amdgcn_exp2f(-delta);
;         m[qn] += delta;
;         lsum[qn] *= alpha;
; #pragma unroll
;         for (int i = 0; i < 16; ++i) { o[qn][0][i] *= alpha; o[qn][1][i] *= alpha; s[qn][0][i] -= delta; s[qn][1][i] -= delta; }
;       }
	v_max3_f32 v216, v193, v192, 0
	v_exp_f32_e64 v222, -v216
	v_sub_f32_e32 v126, v126, v217
	v_sub_f32_e32 v125, v125, v217
	v_sub_f32_e32 v124, v124, v217
	v_sub_f32_e32 v123, v123, v217
	v_sub_f32_e32 v122, v122, v217
	v_sub_f32_e32 v121, v121, v217
	v_sub_f32_e32 v120, v120, v217
	v_sub_f32_e32 v119, v119, v217
	v_sub_f32_e32 v118, v118, v217
	v_sub_f32_e32 v117, v117, v217
	v_sub_f32_e32 v116, v116, v217
	v_sub_f32_e32 v115, v115, v217
	v_sub_f32_e32 v114, v114, v217
	v_sub_f32_e32 v97, v97, v217
	v_sub_f32_e32 v96, v96, v217
	v_sub_f32_e32 v95, v95, v217
	v_sub_f32_e32 v94, v94, v217
	v_sub_f32_e32 v93, v93, v217
	v_sub_f32_e32 v92, v92, v217
	v_sub_f32_e32 v91, v91, v217
	v_sub_f32_e32 v90, v90, v217
	v_sub_f32_e32 v89, v89, v217
	v_sub_f32_e32 v88, v88, v217
	v_sub_f32_e32 v87, v87, v217
	v_sub_f32_e32 v86, v86, v217
	v_sub_f32_e32 v85, v85, v217
	v_sub_f32_e32 v84, v84, v217
	v_sub_f32_e32 v83, v83, v217
	v_sub_f32_e32 v82, v82, v217
	v_pk_add_f32 v[212:213], v[212:213], v[216:217]
	v_pk_mul_f32 v[214:215], v[214:215], v[222:223]
	v_pk_mul_f32 v[16:17], v[16:17], v[222:223] op_sel_hi:[1,0]
	v_pk_mul_f32 v[14:15], v[14:15], v[222:223] op_sel_hi:[1,0]
	v_pk_mul_f32 v[12:13], v[12:13], v[222:223] op_sel_hi:[1,0]
	v_pk_mul_f32 v[10:11], v[10:11], v[222:223] op_sel_hi:[1,0]
	v_pk_mul_f32 v[8:9], v[8:9], v[222:223] op_sel_hi:[1,0]
	v_pk_mul_f32 v[6:7], v[6:7], v[222:223] op_sel_hi:[1,0]
	v_pk_mul_f32 v[4:5], v[4:5], v[222:223] op_sel_hi:[1,0]
	v_pk_mul_f32 v[2:3], v[2:3], v[222:223] op_sel_hi:[1,0]
	v_pk_mul_f32 v[32:33], v[32:33], v[222:223] op_sel_hi:[1,0]
	v_pk_mul_f32 v[30:31], v[30:31], v[222:223] op_sel_hi:[1,0]
	v_pk_mul_f32 v[28:29], v[28:29], v[222:223] op_sel_hi:[1,0]
	v_pk_mul_f32 v[26:27], v[26:27], v[222:223] op_sel_hi:[1,0]
	v_pk_mul_f32 v[24:25], v[24:25], v[222:223] op_sel_hi:[1,0]
	v_pk_mul_f32 v[22:23], v[22:23], v[222:223] op_sel_hi:[1,0]
	v_pk_mul_f32 v[20:21], v[20:21], v[222:223] op_sel_hi:[1,0]
	v_pk_mul_f32 v[18:19], v[18:19], v[222:223] op_sel_hi:[1,0]
	v_sub_f32_e32 v113, v113, v216
	v_sub_f32_e32 v112, v112, v216
	v_sub_f32_e32 v111, v111, v216
	v_sub_f32_e32 v110, v110, v216
	v_sub_f32_e32 v109, v109, v216
	v_sub_f32_e32 v108, v108, v216
	v_sub_f32_e32 v107, v107, v216
	v_sub_f32_e32 v106, v106, v216
	v_sub_f32_e32 v105, v105, v216
	v_sub_f32_e32 v104, v104, v216
	v_sub_f32_e32 v103, v103, v216
	v_sub_f32_e32 v102, v102, v216
	v_sub_f32_e32 v101, v101, v216
	v_sub_f32_e32 v100, v100, v216
	v_sub_f32_e32 v99, v99, v216
	v_sub_f32_e32 v98, v98, v216
	v_sub_f32_e32 v81, v81, v216
	v_sub_f32_e32 v80, v80, v216
	v_sub_f32_e32 v79, v79, v216
	v_sub_f32_e32 v78, v78, v216
	v_sub_f32_e32 v77, v77, v216
	v_sub_f32_e32 v76, v76, v216
	v_sub_f32_e32 v75, v75, v216
	v_sub_f32_e32 v74, v74, v216
	v_sub_f32_e32 v73, v73, v216
	v_sub_f32_e32 v72, v72, v216
	v_sub_f32_e32 v71, v71, v216
	v_sub_f32_e32 v70, v70, v216
	v_sub_f32_e32 v69, v69, v216
	v_sub_f32_e32 v68, v68, v216
	v_sub_f32_e32 v67, v67, v216
	v_sub_f32_e32 v66, v66, v216
	s_branch .LBB0_159
